# combined + F1: SwiGLU GEMM epilogue row-statistics loads issued together instead of eight serialized load-wait rounds
# speedup vs baseline: 1.0141x; 1.0141x over previous
;     __device__ __forceinline__ void operator()(const f32x4 (&acc)[2][2][4][2], const Unit& u, int wr, int wc, int fr, int fq) const {
;         const int row0 = u.pm * BM + wr * 64 + fr, col0 = u.pn * HALF + wc * 32 + 8 * fq, ccol0 = u.pn * BM + wc * 32 + 8 * fq;
;         f32x4 k1[2][2], k2[2][2];
; #pragma unroll
;         for (int bj = 0; bj < 2; ++bj)
; #pragma unroll
;             for (int n = 0; n < 2; ++n) { k1[bj][n] = *(const f32x4*)(c1 + ccol0 + bj * HALF + 4 * n); k2[bj][n] = *(const f32x4*)(c2 + ccol0 + bj * HALF + 4 * n); }
;         float mean8[2][4], rstd8[2][4];
; #pragma unroll
;         for (int ai = 0; ai < 2; ++ai)
; #pragma unroll
;             for (int m = 0; m < 4; ++m) { mean8[ai][m] = st[2 * (row0 + ai * HALF + m * 16)]; rstd8[ai][m] = st[2 * (row0 + ai * HALF + m * 16) + 1]; }
; #pragma unroll
;         for (int ai = 0; ai < 2; ++ai)
; #pragma unroll
;             for (int m = 0; m < 4; ++m) { const float mu = mean8[ai][m] * (1.f / DM); const float var = fmaxf(rstd8[ai][m] * (1.f / DM) - mu * mu, 0.f); mean8[ai][m] = mu; rstd8[ai][m] = rsqrtf(var + LN_EPS); }
; #pragma unroll
;         for (int ai = 0; ai < 2; ++ai)
; #pragma unroll
;             for (int m = 0; m < 4; ++m) { const int row = row0 + ai * HALF + m * 16; bf16_t* rowp = H + (size_t)row * DFF + col0;
;                 const float mean = mean8[ai][m], rstd = rstd8[ai][m];
;                 float h[8];
; #pragma unroll
;                 for (int n = 0; n < 2; ++n) { const f32x4 gq = (acc[ai][0][m][n] - k1[0][n] * mean) * rstd + k2[0][n], uq = (acc[ai][1][m][n] - k1[1][n] * mean) * rstd + k2[1][n];
; #pragma unroll
;                     for (int j = 0; j < 4; ++j) h[n * 4 + j] = gq[j] * __builtin_amdgcn_rcpf(1.f + __expf(-gq[j])) * uq[j]; }
.LBB0_1145:
	v_lshl_add_u32 v213, s87, 8, v179
	v_lshl_or_b32 v52, s86, 8, v185
	v_ashrrev_i32_e32 v53, 31, v52
	v_lshlrev_b32_e32 v174, 1, v213
	v_lshlrev_b64 v[52:53], 2, v[52:53]
	v_ashrrev_i32_e32 v175, 31, v174
	v_lshl_add_u64 v[148:149], s[46:47], 0, v[52:53]
	v_lshl_add_u64 v[156:157], s[58:59], 0, v[52:53]
	v_lshl_add_u64 v[174:175], v[174:175], 2, s[14:15]
	global_load_dwordx4 v[52:55], v[148:149], off offset:16
	global_load_dwordx4 v[68:71], v[148:149], off
	global_load_dwordx4 v[56:59], v[156:157], off offset:16
	global_load_dwordx4 v[72:75], v[156:157], off
	global_load_dwordx4 v[152:155], v[148:149], off offset:528
	global_load_dwordx4 v[160:163], v[148:149], off offset:512
	s_nop 0
	global_load_dwordx4 v[148:151], v[156:157], off offset:528
	s_nop 0
	global_load_dwordx4 v[156:159], v[156:157], off offset:512
	v_mov_b32_e32 v190, v140
	global_load_dwordx2 v[176:177], v[174:175], off
	global_load_dwordx2 v[230:231], v[174:175], off offset:128
	global_load_dwordx2 v[232:233], v[174:175], off offset:256
	global_load_dwordx2 v[234:235], v[174:175], off offset:384
	global_load_dwordx2 v[236:237], v[174:175], off offset:1024
	global_load_dwordx2 v[242:243], v[174:175], off offset:1152
	global_load_dwordx2 v[244:245], v[174:175], off offset:1280
	global_load_dwordx2 v[246:247], v[174:175], off offset:1408
	v_mov_b32_e32 v191, v144
	v_mov_b32_e32 v144, v141
	v_lshl_or_b32 v226, s86, 7, v185
	v_ashrrev_i32_e32 v227, 31, v226
	s_mov_b64 s[16:17], -1
	s_waitcnt vmcnt(0)
	v_mov_b32_e32 v189, v68
	v_mov_b32_e32 v188, v160
	v_pk_mul_f32 v[222:223], v[176:177], s[38:39] op_sel_hi:[1,0]
	s_nop 0
	v_fma_f32 v176, -v222, v222, v223
	v_max_f32_e32 v176, 0, v176
	v_add_f32_e32 v176, 0x3727c5ac, v176
	v_cmp_gt_f32_e32 vcc, s45, v176
	v_mul_f32_e32 v177, 0x4b800000, v176
	v_pk_fma_f32 v[202:203], v[188:189], v[222:223], v[190:191] op_sel_hi:[1,0,1] neg_lo:[1,0,0] neg_hi:[1,0,0]
	v_cndmask_b32_e32 v176, v176, v177, vcc
	v_rsq_f32_e32 v176, v176
	v_mov_b32_e32 v190, v156
	v_mov_b32_e32 v191, v72
	v_mov_b32_e32 v72, v157
	v_mul_f32_e32 v177, 0x45800000, v176
	v_cndmask_b32_e32 v224, v176, v177, vcc
	v_mov_b64_e32 v[176:177], v[230:231]
	v_pk_fma_f32 v[202:203], v[202:203], v[224:225], v[190:191] op_sel_hi:[1,0,1]
	s_waitcnt vmcnt(0)
	v_pk_mul_f32 v[218:219], v[176:177], s[38:39] op_sel_hi:[1,0]
	s_nop 0
	v_fma_f32 v176, -v218, v218, v219
	v_max_f32_e32 v176, 0, v176
	v_add_f32_e32 v176, 0x3727c5ac, v176
	v_cmp_gt_f32_e32 vcc, s45, v176
	v_mul_f32_e32 v177, 0x4b800000, v176
	v_mul_f32_e32 v68, 0xbfb8aa3b, v203
	v_cndmask_b32_e32 v176, v176, v177, vcc
	v_rsq_f32_e32 v176, v176
	v_exp_f32_e32 v68, v68
	v_mul_f32_e32 v177, 0x45800000, v176
	v_cndmask_b32_e32 v220, v176, v177, vcc
	v_mov_b64_e32 v[176:177], v[232:233]
	v_add_f32_e32 v68, 1.0, v68
	v_rcp_f32_e32 v68, v68
	s_waitcnt vmcnt(0)
	v_pk_mul_f32 v[214:215], v[176:177], s[38:39] op_sel_hi:[1,0]
	s_nop 0
	v_fma_f32 v176, -v214, v214, v215
	v_max_f32_e32 v176, 0, v176
	v_add_f32_e32 v176, 0x3727c5ac, v176
	v_cmp_gt_f32_e32 vcc, s45, v176
	v_mul_f32_e32 v177, 0x4b800000, v176
	v_mul_f32_e32 v68, v203, v68
	v_cndmask_b32_e32 v176, v176, v177, vcc
	v_rsq_f32_e32 v176, v176
	v_mul_f32_e32 v160, v202, v68
	v_mov_b32_e32 v68, v161
	v_pk_fma_f32 v[140:141], v[68:69], v[222:223], v[144:145] op_sel_hi:[1,0,1] neg_lo:[1,0,0] neg_hi:[1,0,0]
	v_mul_f32_e32 v177, 0x45800000, v176
	v_cndmask_b32_e32 v216, v176, v177, vcc
	v_mov_b64_e32 v[176:177], v[234:235]
	v_pk_fma_f32 v[140:141], v[140:141], v[224:225], v[72:73] op_sel_hi:[1,0,1]
	v_mov_b32_e32 v145, v146
	v_mul_f32_e32 v144, 0xbfb8aa3b, v141
	v_exp_f32_e32 v144, v144
	v_mov_b32_e32 v146, v143
	v_add_f32_e32 v144, 1.0, v144
	v_rcp_f32_e32 v144, v144
	s_waitcnt vmcnt(0)
	v_pk_mul_f32 v[210:211], v[176:177], s[38:39] op_sel_hi:[1,0]
	s_nop 0
	v_fma_f32 v176, -v210, v210, v211
	v_max_f32_e32 v176, 0, v176
	v_add_f32_e32 v176, 0x3727c5ac, v176
	v_cmp_gt_f32_e32 vcc, s45, v176
	v_mul_f32_e32 v177, 0x4b800000, v176
	v_mul_f32_e32 v141, v141, v144
	v_cndmask_b32_e32 v176, v176, v177, vcc
	v_rsq_f32_e32 v176, v176
	v_mul_f32_e32 v161, v140, v141
	v_mov_b32_e32 v140, v162
	v_mov_b32_e32 v141, v70
	v_mul_f32_e32 v177, 0x45800000, v176
	v_cndmask_b32_e32 v212, v176, v177, vcc
	v_mov_b64_e32 v[176:177], v[236:237]
	v_mov_b32_e32 v144, v142
	v_pk_fma_f32 v[156:157], v[140:141], v[222:223], v[144:145] op_sel_hi:[1,0,1] neg_lo:[1,0,0] neg_hi:[1,0,0]
	v_mov_b32_e32 v144, v158
	v_mov_b32_e32 v145, v74
	v_pk_fma_f32 v[156:157], v[156:157], v[224:225], v[144:145] op_sel_hi:[1,0,1]
	v_mov_b32_e32 v74, v159
	v_mul_f32_e32 v70, 0xbfb8aa3b, v157
	v_exp_f32_e32 v70, v70
	s_waitcnt vmcnt(0)
	v_pk_mul_f32 v[192:193], v[176:177], s[38:39] op_sel_hi:[1,0]
	s_nop 0
	v_fma_f32 v176, -v192, v192, v193
	v_max_f32_e32 v176, 0, v176
	v_add_f32_e32 v176, 0x3727c5ac, v176
	v_cmp_gt_f32_e32 vcc, s45, v176
	v_mul_f32_e32 v177, 0x4b800000, v176
	v_add_f32_e32 v70, 1.0, v70
	v_cndmask_b32_e32 v176, v176, v177, vcc
	v_rsq_f32_e32 v176, v176
	v_rcp_f32_e32 v70, v70
	v_mul_f32_e32 v177, 0x45800000, v176
	v_cndmask_b32_e32 v194, v176, v177, vcc
	v_mov_b64_e32 v[176:177], v[242:243]
	v_mul_f32_e32 v70, v157, v70
	v_mul_f32_e32 v158, v156, v70
	v_mov_b32_e32 v70, v163
	v_pk_fma_f32 v[142:143], v[70:71], v[222:223], v[146:147] op_sel_hi:[1,0,1] neg_lo:[1,0,0] neg_hi:[1,0,0]
	v_mov_b32_e32 v147, v136
	v_pk_fma_f32 v[142:143], v[142:143], v[224:225], v[74:75] op_sel_hi:[1,0,1]
	v_mov_b32_e32 v136, v133
	v_mul_f32_e32 v146, 0xbfb8aa3b, v143
	v_exp_f32_e32 v146, v146
	s_waitcnt vmcnt(0)
; __device__ __forceinline__ unsigned cvt_pk_bf16(float lo, float hi) { unsigned r; asm volatile("v_cvt_pk_bf16_f32 %0, %1, %2" : "=v"(r) : "v"(lo), "v"(hi)); return r; }
;     __device__ __forceinline__ void operator()(const f32x4 (&acc)[2][2][4][2], const Unit& u, int wr, int wc, int fr, int fq) const {
;     ...
;             for (int m = 0; m < 4; ++m) { const float mu = mean8[ai][m] * (1.f / DM); const float var = fmaxf(rstd8[ai][m] * (1.f / DM) - mu * mu, 0.f); mean8[ai][m] = mu; rstd8[ai][m] = rsqrtf(var + LN_EPS); }
; #pragma unroll
;         for (int ai = 0; ai < 2; ++ai)
; #pragma unroll
;             for (int m = 0; m < 4; ++m) { const int row = row0 + ai * HALF + m * 16; bf16_t* rowp = H + (size_t)row * DFF + col0;
;                 const float mean = mean8[ai][m], rstd = rstd8[ai][m];
;                 float h[8];
; #pragma unroll
;                 for (int n = 0; n < 2; ++n) { const f32x4 gq = (acc[ai][0][m][n] - k1[0][n] * mean) * rstd + k2[0][n], uq = (acc[ai][1][m][n] - k1[1][n] * mean) * rstd + k2[1][n];
; #pragma unroll
;                     for (int j = 0; j < 4; ++j) h[n * 4 + j] = gq[j] * __builtin_amdgcn_rcpf(1.f + __expf(-gq[j])) * uq[j]; }
;                 u32x4 w; w.x = cvt_pk_bf16(h[0], h[1]); w.y = cvt_pk_bf16(h[2], h[3]); w.z = cvt_pk_bf16(h[4], h[5]); w.w = cvt_pk_bf16(h[6], h[7]);
;                 *(u32x4*)rowp = w; }
	v_pk_mul_f32 v[182:183], v[176:177], s[38:39] op_sel_hi:[1,0]
	s_nop 0
	v_fma_f32 v176, -v182, v182, v183
	v_max_f32_e32 v176, 0, v176
	v_add_f32_e32 v176, 0x3727c5ac, v176
	v_cmp_gt_f32_e32 vcc, s45, v176
	v_mul_f32_e32 v177, 0x4b800000, v176
	v_add_f32_e32 v146, 1.0, v146
	v_cndmask_b32_e32 v176, v176, v177, vcc
	v_rsq_f32_e32 v176, v176
	v_rcp_f32_e32 v146, v146
	v_mul_f32_e32 v177, 0x45800000, v176
	v_cndmask_b32_e32 v184, v176, v177, vcc
	v_mov_b64_e32 v[176:177], v[244:245]
	v_mul_f32_e32 v143, v143, v146
	v_mov_b64_e32 v[174:175], v[246:247]
	v_mul_f32_e32 v159, v142, v143
	v_mov_b32_e32 v142, v152
	v_mov_b32_e32 v143, v52
	v_mov_b32_e32 v146, v132
	v_pk_fma_f32 v[156:157], v[142:143], v[222:223], v[146:147] op_sel_hi:[1,0,1] neg_lo:[1,0,0] neg_hi:[1,0,0]
	v_mov_b32_e32 v146, v148
	v_mov_b32_e32 v147, v56
	v_pk_fma_f32 v[156:157], v[156:157], v[224:225], v[146:147] op_sel_hi:[1,0,1]
	v_mov_b32_e32 v56, v149
	v_mul_f32_e32 v52, 0xbfb8aa3b, v157
	v_exp_f32_e32 v52, v52
	s_waitcnt vmcnt(1)
	v_pk_mul_f32 v[176:177], v[176:177], s[38:39] op_sel_hi:[1,0]
	v_add_f32_e32 v52, 1.0, v52
	v_rcp_f32_e32 v52, v52
	v_fma_f32 v178, -v176, v176, v177
	v_max_f32_e32 v178, 0, v178
	v_add_f32_e32 v178, 0x3727c5ac, v178
	v_mul_f32_e32 v52, v157, v52
	v_mul_f32_e32 v152, v156, v52
	v_mov_b32_e32 v52, v153
	v_pk_fma_f32 v[132:133], v[52:53], v[222:223], v[136:137] op_sel_hi:[1,0,1] neg_lo:[1,0,0] neg_hi:[1,0,0]
	v_mov_b32_e32 v137, v138
	v_pk_fma_f32 v[132:133], v[132:133], v[224:225], v[56:57] op_sel_hi:[1,0,1]
	v_cmp_gt_f32_e32 vcc, s45, v178
	v_mul_f32_e32 v136, 0xbfb8aa3b, v133
	v_exp_f32_e32 v136, v136
	v_mul_f32_e32 v180, 0x4b800000, v178
	v_cndmask_b32_e32 v178, v178, v180, vcc
	v_rsq_f32_e32 v178, v178
	v_add_f32_e32 v136, 1.0, v136
	v_rcp_f32_e32 v136, v136
	v_mov_b32_e32 v138, v135
	v_mul_f32_e32 v180, 0x45800000, v178
	s_waitcnt vmcnt(0)
	v_pk_mul_f32 v[174:175], v[174:175], s[38:39] op_sel_hi:[1,0]
	v_mul_f32_e32 v133, v133, v136
	v_mul_f32_e32 v153, v132, v133
	v_mov_b32_e32 v132, v154
	v_mov_b32_e32 v133, v54
	v_mov_b32_e32 v136, v134
	v_pk_fma_f32 v[148:149], v[132:133], v[222:223], v[136:137] op_sel_hi:[1,0,1] neg_lo:[1,0,0] neg_hi:[1,0,0]
	v_mov_b32_e32 v136, v150
	v_mov_b32_e32 v137, v58
	v_pk_fma_f32 v[148:149], v[148:149], v[224:225], v[136:137] op_sel_hi:[1,0,1]
	v_mov_b32_e32 v58, v151
	v_mul_f32_e32 v54, 0xbfb8aa3b, v149
	v_exp_f32_e32 v54, v54
	v_cndmask_b32_e32 v178, v178, v180, vcc
	v_fma_f32 v180, -v174, v174, v175
	v_max_f32_e32 v180, 0, v180
	v_add_f32_e32 v54, 1.0, v54
	v_rcp_f32_e32 v54, v54
	v_add_f32_e32 v180, 0x3727c5ac, v180
	v_cmp_gt_f32_e32 vcc, s45, v180
	v_mul_f32_e32 v186, 0x4b800000, v180
	v_mul_f32_e32 v54, v149, v54
	v_mul_f32_e32 v154, v148, v54
	v_mov_b32_e32 v54, v155
	v_pk_fma_f32 v[134:135], v[54:55], v[222:223], v[138:139] op_sel_hi:[1,0,1] neg_lo:[1,0,0] neg_hi:[1,0,0]
	v_cndmask_b32_e32 v180, v180, v186, vcc
	v_pk_fma_f32 v[134:135], v[134:135], v[224:225], v[58:59] op_sel_hi:[1,0,1]
	v_rsq_f32_e32 v180, v180
	v_mul_f32_e32 v138, 0xbfb8aa3b, v135
	v_exp_f32_e32 v138, v138
	v_cvt_pk_bf16_f32 v148, v160, v161
	v_mul_f32_e32 v186, 0x45800000, v180
	v_cndmask_b32_e32 v180, v180, v186, vcc
	v_add_f32_e32 v138, 1.0, v138
	v_rcp_f32_e32 v138, v138
	v_mov_b64_e32 v[186:187], s[6:7]
	v_mad_i64_i32 v[228:229], s[10:11], v213, s51, v[186:187]
	v_mul_f32_e32 v135, v135, v138
	v_mul_f32_e32 v151, v134, v135
	v_lshlrev_b64 v[134:135], 1, v[226:227]
	v_lshl_add_u64 v[138:139], v[228:229], 0, v[134:135]
	v_cvt_pk_bf16_f32 v149, v158, v159
	v_cvt_pk_bf16_f32 v150, v152, v153
	v_cvt_pk_bf16_f32 v151, v154, v151
	global_store_dwordx4 v[138:139], v[148:151], off
	v_or_b32_e32 v138, 16, v213
	v_mad_i64_i32 v[138:139], s[10:11], v138, s51, v[186:187]
	v_mov_b32_e32 v148, v124
	v_mov_b32_e32 v149, v128
	v_pk_fma_f32 v[148:149], v[188:189], v[218:219], v[148:149] op_sel_hi:[1,0,1] neg_lo:[1,0,0] neg_hi:[1,0,0]
	v_mov_b32_e32 v128, v125
	v_pk_fma_f32 v[148:149], v[148:149], v[220:221], v[190:191] op_sel_hi:[1,0,1]
	s_andn2_b64 vcc, exec, s[2:3]
	v_mul_f32_e32 v124, 0xbfb8aa3b, v149
	v_exp_f32_e32 v124, v124
	s_nop 0
	v_add_f32_e32 v124, 1.0, v124
	v_rcp_f32_e32 v124, v124
	s_nop 0
	v_mul_f32_e32 v124, v149, v124
	v_mul_f32_e32 v148, v148, v124
	v_pk_fma_f32 v[124:125], v[68:69], v[218:219], v[128:129] op_sel_hi:[1,0,1] neg_lo:[1,0,0] neg_hi:[1,0,0]
	s_nop 0
	v_pk_fma_f32 v[124:125], v[124:125], v[220:221], v[72:73] op_sel_hi:[1,0,1]
	s_nop 0
	v_mul_f32_e32 v128, 0xbfb8aa3b, v125
	v_exp_f32_e32 v128, v128
	s_nop 0
	v_add_f32_e32 v128, 1.0, v128
	v_rcp_f32_e32 v128, v128
	s_nop 0
	v_mul_f32_e32 v125, v125, v128
	v_mul_f32_e32 v128, v124, v125
	v_mov_b32_e32 v124, v126
	v_mov_b32_e32 v125, v130
	v_pk_fma_f32 v[124:125], v[140:141], v[218:219], v[124:125] op_sel_hi:[1,0,1] neg_lo:[1,0,0] neg_hi:[1,0,0]
	v_mov_b32_e32 v130, v127
	v_pk_fma_f32 v[124:125], v[124:125], v[220:221], v[144:145] op_sel_hi:[1,0,1]
	s_nop 0
	v_mul_f32_e32 v126, 0xbfb8aa3b, v125
	v_exp_f32_e32 v126, v126
	s_nop 0
	v_add_f32_e32 v126, 1.0, v126
	v_rcp_f32_e32 v126, v126
	s_nop 0
	v_mul_f32_e32 v125, v125, v126
	v_mul_f32_e32 v126, v124, v125
	v_pk_fma_f32 v[124:125], v[70:71], v[218:219], v[130:131] op_sel_hi:[1,0,1] neg_lo:[1,0,0] neg_hi:[1,0,0]
	s_nop 0
	v_pk_fma_f32 v[124:125], v[124:125], v[220:221], v[74:75] op_sel_hi:[1,0,1]
	s_nop 0
	v_mul_f32_e32 v127, 0xbfb8aa3b, v125
	v_exp_f32_e32 v127, v127
	s_nop 0
	v_add_f32_e32 v127, 1.0, v127
	v_rcp_f32_e32 v127, v127
	s_nop 0
	v_mul_f32_e32 v125, v125, v127
	v_mul_f32_e32 v127, v124, v125
	v_mov_b32_e32 v124, v116
	v_mov_b32_e32 v125, v120
	v_pk_fma_f32 v[124:125], v[142:143], v[218:219], v[124:125] op_sel_hi:[1,0,1] neg_lo:[1,0,0] neg_hi:[1,0,0]
; __device__ __forceinline__ unsigned cvt_pk_bf16(float lo, float hi) { unsigned r; asm volatile("v_cvt_pk_bf16_f32 %0, %1, %2" : "=v"(r) : "v"(lo), "v"(hi)); return r; }
;     __device__ __forceinline__ void operator()(const f32x4 (&acc)[2][2][4][2], const Unit& u, int wr, int wc, int fr, int fq) const {
;     ...
;             for (int m = 0; m < 4; ++m) { const int row = row0 + ai * HALF + m * 16; bf16_t* rowp = H + (size_t)row * DFF + col0;
;                 const float mean = mean8[ai][m], rstd = rstd8[ai][m];
;                 float h[8];
; #pragma unroll
;                 for (int n = 0; n < 2; ++n) { const f32x4 gq = (acc[ai][0][m][n] - k1[0][n] * mean) * rstd + k2[0][n], uq = (acc[ai][1][m][n] - k1[1][n] * mean) * rstd + k2[1][n];
; #pragma unroll
;                     for (int j = 0; j < 4; ++j) h[n * 4 + j] = gq[j] * __builtin_amdgcn_rcpf(1.f + __expf(-gq[j])) * uq[j]; }
;                 u32x4 w; w.x = cvt_pk_bf16(h[0], h[1]); w.y = cvt_pk_bf16(h[2], h[3]); w.z = cvt_pk_bf16(h[4], h[5]); w.w = cvt_pk_bf16(h[6], h[7]);
;                 *(u32x4*)rowp = w; }
	v_mov_b32_e32 v120, v117
	v_pk_fma_f32 v[124:125], v[124:125], v[220:221], v[146:147] op_sel_hi:[1,0,1]
	s_nop 0
	v_mul_f32_e32 v116, 0xbfb8aa3b, v125
	v_exp_f32_e32 v116, v116
	s_nop 0
	v_add_f32_e32 v116, 1.0, v116
	v_rcp_f32_e32 v116, v116
	s_nop 0
	v_mul_f32_e32 v116, v125, v116
	v_mul_f32_e32 v124, v124, v116
	v_pk_fma_f32 v[116:117], v[52:53], v[218:219], v[120:121] op_sel_hi:[1,0,1] neg_lo:[1,0,0] neg_hi:[1,0,0]
	s_nop 0
	v_pk_fma_f32 v[116:117], v[116:117], v[220:221], v[56:57] op_sel_hi:[1,0,1]
	s_nop 0
	v_mul_f32_e32 v120, 0xbfb8aa3b, v117
	v_exp_f32_e32 v120, v120
	s_nop 0
	v_add_f32_e32 v120, 1.0, v120
	v_rcp_f32_e32 v120, v120
	s_nop 0
	v_mul_f32_e32 v117, v117, v120
	v_mul_f32_e32 v125, v116, v117
	v_mov_b32_e32 v116, v118
	v_mov_b32_e32 v117, v122
	v_pk_fma_f32 v[116:117], v[132:133], v[218:219], v[116:117] op_sel_hi:[1,0,1] neg_lo:[1,0,0] neg_hi:[1,0,0]
	v_mov_b32_e32 v122, v119
	v_pk_fma_f32 v[116:117], v[116:117], v[220:221], v[136:137] op_sel_hi:[1,0,1]
	v_lshl_add_u64 v[120:121], v[138:139], 0, v[134:135]
	v_mul_f32_e32 v118, 0xbfb8aa3b, v117
	v_exp_f32_e32 v118, v118
	s_nop 0
	v_add_f32_e32 v118, 1.0, v118
	v_rcp_f32_e32 v118, v118
	s_nop 0
	v_mul_f32_e32 v117, v117, v118
	v_mul_f32_e32 v129, v116, v117
	v_pk_fma_f32 v[116:117], v[54:55], v[218:219], v[122:123] op_sel_hi:[1,0,1] neg_lo:[1,0,0] neg_hi:[1,0,0]
	s_nop 0
	v_pk_fma_f32 v[116:117], v[116:117], v[220:221], v[58:59] op_sel_hi:[1,0,1]
	s_nop 0
	v_mul_f32_e32 v118, 0xbfb8aa3b, v117
	v_exp_f32_e32 v118, v118
	s_nop 0
	v_add_f32_e32 v118, 1.0, v118
	v_rcp_f32_e32 v118, v118
	s_nop 0
	v_mul_f32_e32 v117, v117, v118
	v_mul_f32_e32 v119, v116, v117
	v_cvt_pk_bf16_f32 v116, v148, v128
	v_cvt_pk_bf16_f32 v117, v126, v127
	v_cvt_pk_bf16_f32 v118, v124, v125
	v_cvt_pk_bf16_f32 v119, v129, v119
	global_store_dwordx4 v[120:121], v[116:119], off
	s_nop 1
	v_mov_b32_e32 v118, v108
	v_mov_b32_e32 v119, v112
	v_pk_fma_f32 v[118:119], v[188:189], v[214:215], v[118:119] op_sel_hi:[1,0,1] neg_lo:[1,0,0] neg_hi:[1,0,0]
	v_mov_b32_e32 v112, v109
	v_pk_fma_f32 v[118:119], v[118:119], v[216:217], v[190:191] op_sel_hi:[1,0,1]
	v_or_b32_e32 v116, 32, v213
	v_mul_f32_e32 v108, 0xbfb8aa3b, v119
	v_exp_f32_e32 v108, v108
	v_mad_i64_i32 v[116:117], s[10:11], v116, s51, v[186:187]
	v_add_f32_e32 v108, 1.0, v108
	v_rcp_f32_e32 v108, v108
	s_nop 0
	v_mul_f32_e32 v108, v119, v108
	v_mul_f32_e32 v118, v118, v108
	v_pk_fma_f32 v[108:109], v[68:69], v[214:215], v[112:113] op_sel_hi:[1,0,1] neg_lo:[1,0,0] neg_hi:[1,0,0]
	s_nop 0
	v_pk_fma_f32 v[108:109], v[108:109], v[216:217], v[72:73] op_sel_hi:[1,0,1]
	s_nop 0
	v_mul_f32_e32 v112, 0xbfb8aa3b, v109
	v_exp_f32_e32 v112, v112
	s_nop 0
	v_add_f32_e32 v112, 1.0, v112
	v_rcp_f32_e32 v112, v112
	s_nop 0
	v_mul_f32_e32 v109, v109, v112
	v_mul_f32_e32 v112, v108, v109
	v_mov_b32_e32 v108, v110
	v_mov_b32_e32 v109, v114
	v_pk_fma_f32 v[108:109], v[140:141], v[214:215], v[108:109] op_sel_hi:[1,0,1] neg_lo:[1,0,0] neg_hi:[1,0,0]
	v_mov_b32_e32 v114, v111
	v_pk_fma_f32 v[108:109], v[108:109], v[216:217], v[144:145] op_sel_hi:[1,0,1]
	s_nop 0
	v_mul_f32_e32 v110, 0xbfb8aa3b, v109
	v_exp_f32_e32 v110, v110
	s_nop 0
	v_add_f32_e32 v110, 1.0, v110
	v_rcp_f32_e32 v110, v110
	s_nop 0
	v_mul_f32_e32 v109, v109, v110
	v_mul_f32_e32 v110, v108, v109
	v_pk_fma_f32 v[108:109], v[70:71], v[214:215], v[114:115] op_sel_hi:[1,0,1] neg_lo:[1,0,0] neg_hi:[1,0,0]
	s_nop 0
	v_pk_fma_f32 v[108:109], v[108:109], v[216:217], v[74:75] op_sel_hi:[1,0,1]
	s_nop 0
	v_mul_f32_e32 v111, 0xbfb8aa3b, v109
	v_exp_f32_e32 v111, v111
	s_nop 0
	v_add_f32_e32 v111, 1.0, v111
	v_rcp_f32_e32 v111, v111
	s_nop 0
	v_mul_f32_e32 v109, v109, v111
	v_mul_f32_e32 v111, v108, v109
	v_mov_b32_e32 v108, v100
	v_mov_b32_e32 v109, v104
	v_pk_fma_f32 v[108:109], v[142:143], v[214:215], v[108:109] op_sel_hi:[1,0,1] neg_lo:[1,0,0] neg_hi:[1,0,0]
	v_mov_b32_e32 v104, v101
	v_pk_fma_f32 v[108:109], v[108:109], v[216:217], v[146:147] op_sel_hi:[1,0,1]
	s_nop 0
	v_mul_f32_e32 v100, 0xbfb8aa3b, v109
	v_exp_f32_e32 v100, v100
	s_nop 0
	v_add_f32_e32 v100, 1.0, v100
	v_rcp_f32_e32 v100, v100
	s_nop 0
	v_mul_f32_e32 v100, v109, v100
	v_mul_f32_e32 v108, v108, v100
	v_pk_fma_f32 v[100:101], v[52:53], v[214:215], v[104:105] op_sel_hi:[1,0,1] neg_lo:[1,0,0] neg_hi:[1,0,0]
	s_nop 0
	v_pk_fma_f32 v[100:101], v[100:101], v[216:217], v[56:57] op_sel_hi:[1,0,1]
	s_nop 0
	v_mul_f32_e32 v104, 0xbfb8aa3b, v101
	v_exp_f32_e32 v104, v104
	s_nop 0
	v_add_f32_e32 v104, 1.0, v104
	v_rcp_f32_e32 v104, v104
	s_nop 0
	v_mul_f32_e32 v101, v101, v104
	v_mul_f32_e32 v109, v100, v101
	v_mov_b32_e32 v100, v102
	v_mov_b32_e32 v101, v106
	v_pk_fma_f32 v[100:101], v[132:133], v[214:215], v[100:101] op_sel_hi:[1,0,1] neg_lo:[1,0,0] neg_hi:[1,0,0]
	v_mov_b32_e32 v106, v103
	v_pk_fma_f32 v[100:101], v[100:101], v[216:217], v[136:137] op_sel_hi:[1,0,1]
	v_lshl_add_u64 v[104:105], v[116:117], 0, v[134:135]
	v_mul_f32_e32 v102, 0xbfb8aa3b, v101
	v_exp_f32_e32 v102, v102
	s_nop 0
	v_add_f32_e32 v102, 1.0, v102
	v_rcp_f32_e32 v102, v102
	s_nop 0
	v_mul_f32_e32 v101, v101, v102
	v_mul_f32_e32 v113, v100, v101
	v_pk_fma_f32 v[100:101], v[54:55], v[214:215], v[106:107] op_sel_hi:[1,0,1] neg_lo:[1,0,0] neg_hi:[1,0,0]
	s_nop 0
	v_pk_fma_f32 v[100:101], v[100:101], v[216:217], v[58:59] op_sel_hi:[1,0,1]
	s_nop 0
	v_mul_f32_e32 v102, 0xbfb8aa3b, v101
	v_exp_f32_e32 v102, v102
	s_nop 0
	v_add_f32_e32 v102, 1.0, v102
	v_rcp_f32_e32 v102, v102
	s_nop 0
	v_mul_f32_e32 v101, v101, v102
	v_mul_f32_e32 v103, v100, v101
	v_cvt_pk_bf16_f32 v100, v118, v112
	v_cvt_pk_bf16_f32 v101, v110, v111
	v_cvt_pk_bf16_f32 v102, v108, v109
	v_cvt_pk_bf16_f32 v103, v113, v103
; __device__ __forceinline__ unsigned cvt_pk_bf16(float lo, float hi) { unsigned r; asm volatile("v_cvt_pk_bf16_f32 %0, %1, %2" : "=v"(r) : "v"(lo), "v"(hi)); return r; }
;     __device__ __forceinline__ void operator()(const f32x4 (&acc)[2][2][4][2], const Unit& u, int wr, int wc, int fr, int fq) const {
;     ...
;             for (int m = 0; m < 4; ++m) { const int row = row0 + ai * HALF + m * 16; bf16_t* rowp = H + (size_t)row * DFF + col0;
;                 const float mean = mean8[ai][m], rstd = rstd8[ai][m];
;                 float h[8];
; #pragma unroll
;                 for (int n = 0; n < 2; ++n) { const f32x4 gq = (acc[ai][0][m][n] - k1[0][n] * mean) * rstd + k2[0][n], uq = (acc[ai][1][m][n] - k1[1][n] * mean) * rstd + k2[1][n];
; #pragma unroll
;                     for (int j = 0; j < 4; ++j) h[n * 4 + j] = gq[j] * __builtin_amdgcn_rcpf(1.f + __expf(-gq[j])) * uq[j]; }
;                 u32x4 w; w.x = cvt_pk_bf16(h[0], h[1]); w.y = cvt_pk_bf16(h[2], h[3]); w.z = cvt_pk_bf16(h[4], h[5]); w.w = cvt_pk_bf16(h[6], h[7]);
;                 *(u32x4*)rowp = w; }
	global_store_dwordx4 v[104:105], v[100:103], off
	s_nop 1
	v_mov_b32_e32 v102, v92
	v_mov_b32_e32 v103, v96
	v_pk_fma_f32 v[102:103], v[188:189], v[210:211], v[102:103] op_sel_hi:[1,0,1] neg_lo:[1,0,0] neg_hi:[1,0,0]
	v_mov_b32_e32 v96, v93
	v_pk_fma_f32 v[102:103], v[102:103], v[212:213], v[190:191] op_sel_hi:[1,0,1]
	v_or_b32_e32 v100, 48, v213
	v_mul_f32_e32 v92, 0xbfb8aa3b, v103
	v_exp_f32_e32 v92, v92
	v_mad_i64_i32 v[100:101], s[10:11], v100, s51, v[186:187]
	v_add_f32_e32 v92, 1.0, v92
	v_rcp_f32_e32 v92, v92
	s_nop 0
	v_mul_f32_e32 v92, v103, v92
	v_mul_f32_e32 v102, v102, v92
	v_pk_fma_f32 v[92:93], v[68:69], v[210:211], v[96:97] op_sel_hi:[1,0,1] neg_lo:[1,0,0] neg_hi:[1,0,0]
	s_nop 0
	v_pk_fma_f32 v[92:93], v[92:93], v[212:213], v[72:73] op_sel_hi:[1,0,1]
	s_nop 0
	v_mul_f32_e32 v96, 0xbfb8aa3b, v93
	v_exp_f32_e32 v96, v96
	s_nop 0
	v_add_f32_e32 v96, 1.0, v96
	v_rcp_f32_e32 v96, v96
	s_nop 0
	v_mul_f32_e32 v93, v93, v96
	v_mul_f32_e32 v96, v92, v93
	v_mov_b32_e32 v92, v94
	v_mov_b32_e32 v93, v98
	v_pk_fma_f32 v[92:93], v[140:141], v[210:211], v[92:93] op_sel_hi:[1,0,1] neg_lo:[1,0,0] neg_hi:[1,0,0]
	v_mov_b32_e32 v98, v95
	v_pk_fma_f32 v[92:93], v[92:93], v[212:213], v[144:145] op_sel_hi:[1,0,1]
	s_nop 0
	v_mul_f32_e32 v94, 0xbfb8aa3b, v93
	v_exp_f32_e32 v94, v94
	s_nop 0
	v_add_f32_e32 v94, 1.0, v94
	v_rcp_f32_e32 v94, v94
	s_nop 0
	v_mul_f32_e32 v93, v93, v94
	v_mul_f32_e32 v94, v92, v93
	v_pk_fma_f32 v[92:93], v[70:71], v[210:211], v[98:99] op_sel_hi:[1,0,1] neg_lo:[1,0,0] neg_hi:[1,0,0]
	s_nop 0
	v_pk_fma_f32 v[92:93], v[92:93], v[212:213], v[74:75] op_sel_hi:[1,0,1]
	s_nop 0
	v_mul_f32_e32 v95, 0xbfb8aa3b, v93
	v_exp_f32_e32 v95, v95
	s_nop 0
	v_add_f32_e32 v95, 1.0, v95
	v_rcp_f32_e32 v95, v95
	s_nop 0
	v_mul_f32_e32 v93, v93, v95
	v_mul_f32_e32 v95, v92, v93
	v_mov_b32_e32 v92, v84
	v_mov_b32_e32 v93, v88
	v_pk_fma_f32 v[92:93], v[142:143], v[210:211], v[92:93] op_sel_hi:[1,0,1] neg_lo:[1,0,0] neg_hi:[1,0,0]
	v_mov_b32_e32 v88, v85
	v_pk_fma_f32 v[92:93], v[92:93], v[212:213], v[146:147] op_sel_hi:[1,0,1]
	s_nop 0
	v_mul_f32_e32 v84, 0xbfb8aa3b, v93
	v_exp_f32_e32 v84, v84
	s_nop 0
	v_add_f32_e32 v84, 1.0, v84
	v_rcp_f32_e32 v84, v84
	s_nop 0
	v_mul_f32_e32 v84, v93, v84
	v_mul_f32_e32 v92, v92, v84
	v_pk_fma_f32 v[84:85], v[52:53], v[210:211], v[88:89] op_sel_hi:[1,0,1] neg_lo:[1,0,0] neg_hi:[1,0,0]
	s_nop 0
	v_pk_fma_f32 v[84:85], v[84:85], v[212:213], v[56:57] op_sel_hi:[1,0,1]
	s_nop 0
	v_mul_f32_e32 v88, 0xbfb8aa3b, v85
	v_exp_f32_e32 v88, v88
	s_nop 0
	v_add_f32_e32 v88, 1.0, v88
	v_rcp_f32_e32 v88, v88
	s_nop 0
	v_mul_f32_e32 v85, v85, v88
	v_mul_f32_e32 v93, v84, v85
	v_mov_b32_e32 v84, v86
	v_mov_b32_e32 v85, v90
	v_pk_fma_f32 v[84:85], v[132:133], v[210:211], v[84:85] op_sel_hi:[1,0,1] neg_lo:[1,0,0] neg_hi:[1,0,0]
	v_mov_b32_e32 v90, v87
	v_pk_fma_f32 v[84:85], v[84:85], v[212:213], v[136:137] op_sel_hi:[1,0,1]
	v_lshl_add_u64 v[88:89], v[100:101], 0, v[134:135]
	v_mul_f32_e32 v86, 0xbfb8aa3b, v85
	v_exp_f32_e32 v86, v86
	s_nop 0
	v_add_f32_e32 v86, 1.0, v86
	v_rcp_f32_e32 v86, v86
	s_nop 0
	v_mul_f32_e32 v85, v85, v86
	v_mul_f32_e32 v97, v84, v85
	v_pk_fma_f32 v[84:85], v[54:55], v[210:211], v[90:91] op_sel_hi:[1,0,1] neg_lo:[1,0,0] neg_hi:[1,0,0]
	s_nop 0
	v_pk_fma_f32 v[84:85], v[84:85], v[212:213], v[58:59] op_sel_hi:[1,0,1]
	s_nop 0
	v_mul_f32_e32 v86, 0xbfb8aa3b, v85
	v_exp_f32_e32 v86, v86
	s_nop 0
	v_add_f32_e32 v86, 1.0, v86
	v_rcp_f32_e32 v86, v86
	s_nop 0
	v_mul_f32_e32 v85, v85, v86
	v_mul_f32_e32 v87, v84, v85
	v_cvt_pk_bf16_f32 v84, v102, v96
	v_cvt_pk_bf16_f32 v85, v94, v95
	v_cvt_pk_bf16_f32 v86, v92, v93
	v_cvt_pk_bf16_f32 v87, v97, v87
	global_store_dwordx4 v[88:89], v[84:87], off
	s_nop 1
	v_mov_b32_e32 v86, v76
	v_mov_b32_e32 v87, v80
	v_pk_fma_f32 v[86:87], v[188:189], v[192:193], v[86:87] op_sel_hi:[1,0,1] neg_lo:[1,0,0] neg_hi:[1,0,0]
	v_mov_b32_e32 v80, v77
	v_pk_fma_f32 v[86:87], v[86:87], v[194:195], v[190:191] op_sel_hi:[1,0,1]
	v_add_u32_e32 v84, 0x80, v213
	v_mul_f32_e32 v76, 0xbfb8aa3b, v87
	v_exp_f32_e32 v76, v76
	v_mad_i64_i32 v[84:85], s[10:11], v84, s51, v[186:187]
	v_add_f32_e32 v76, 1.0, v76
	v_rcp_f32_e32 v76, v76
	s_nop 0
	v_mul_f32_e32 v76, v87, v76
	v_mul_f32_e32 v86, v86, v76
	v_pk_fma_f32 v[76:77], v[68:69], v[192:193], v[80:81] op_sel_hi:[1,0,1] neg_lo:[1,0,0] neg_hi:[1,0,0]
	s_nop 0
	v_pk_fma_f32 v[76:77], v[76:77], v[194:195], v[72:73] op_sel_hi:[1,0,1]
	s_nop 0
	v_mul_f32_e32 v80, 0xbfb8aa3b, v77
	v_exp_f32_e32 v80, v80
	s_nop 0
	v_add_f32_e32 v80, 1.0, v80
	v_rcp_f32_e32 v80, v80
	s_nop 0
	v_mul_f32_e32 v77, v77, v80
	v_mul_f32_e32 v80, v76, v77
	v_mov_b32_e32 v76, v78
	v_mov_b32_e32 v77, v82
	v_pk_fma_f32 v[76:77], v[140:141], v[192:193], v[76:77] op_sel_hi:[1,0,1] neg_lo:[1,0,0] neg_hi:[1,0,0]
	v_mov_b32_e32 v82, v79
	v_pk_fma_f32 v[76:77], v[76:77], v[194:195], v[144:145] op_sel_hi:[1,0,1]
	s_nop 0
	v_mul_f32_e32 v78, 0xbfb8aa3b, v77
	v_exp_f32_e32 v78, v78
	s_nop 0
	v_add_f32_e32 v78, 1.0, v78
	v_rcp_f32_e32 v78, v78
	s_nop 0
	v_mul_f32_e32 v77, v77, v78
	v_mul_f32_e32 v78, v76, v77
	v_pk_fma_f32 v[76:77], v[70:71], v[192:193], v[82:83] op_sel_hi:[1,0,1] neg_lo:[1,0,0] neg_hi:[1,0,0]
	s_nop 0
	v_pk_fma_f32 v[76:77], v[76:77], v[194:195], v[74:75] op_sel_hi:[1,0,1]
	s_nop 0
	v_mul_f32_e32 v79, 0xbfb8aa3b, v77
	v_exp_f32_e32 v79, v79
	s_nop 0
	v_add_f32_e32 v79, 1.0, v79
	v_rcp_f32_e32 v79, v79
	s_nop 0
	v_mul_f32_e32 v77, v77, v79
	v_mul_f32_e32 v79, v76, v77
	v_mov_b32_e32 v76, v60
	v_mov_b32_e32 v77, v64
	v_pk_fma_f32 v[76:77], v[142:143], v[192:193], v[76:77] op_sel_hi:[1,0,1] neg_lo:[1,0,0] neg_hi:[1,0,0]
	v_mov_b32_e32 v64, v61
; __device__ __forceinline__ unsigned cvt_pk_bf16(float lo, float hi) { unsigned r; asm volatile("v_cvt_pk_bf16_f32 %0, %1, %2" : "=v"(r) : "v"(lo), "v"(hi)); return r; }
;     __device__ __forceinline__ void operator()(const f32x4 (&acc)[2][2][4][2], const Unit& u, int wr, int wc, int fr, int fq) const {
;     ...
;             for (int m = 0; m < 4; ++m) { const int row = row0 + ai * HALF + m * 16; bf16_t* rowp = H + (size_t)row * DFF + col0;
;                 const float mean = mean8[ai][m], rstd = rstd8[ai][m];
;                 float h[8];
; #pragma unroll
;                 for (int n = 0; n < 2; ++n) { const f32x4 gq = (acc[ai][0][m][n] - k1[0][n] * mean) * rstd + k2[0][n], uq = (acc[ai][1][m][n] - k1[1][n] * mean) * rstd + k2[1][n];
; #pragma unroll
;                     for (int j = 0; j < 4; ++j) h[n * 4 + j] = gq[j] * __builtin_amdgcn_rcpf(1.f + __expf(-gq[j])) * uq[j]; }
;                 u32x4 w; w.x = cvt_pk_bf16(h[0], h[1]); w.y = cvt_pk_bf16(h[2], h[3]); w.z = cvt_pk_bf16(h[4], h[5]); w.w = cvt_pk_bf16(h[6], h[7]);
;                 *(u32x4*)rowp = w; }
	v_pk_fma_f32 v[76:77], v[76:77], v[194:195], v[146:147] op_sel_hi:[1,0,1]
	s_nop 0
	v_mul_f32_e32 v60, 0xbfb8aa3b, v77
	v_exp_f32_e32 v60, v60
	s_nop 0
	v_add_f32_e32 v60, 1.0, v60
	v_rcp_f32_e32 v60, v60
	s_nop 0
	v_mul_f32_e32 v60, v77, v60
	v_mul_f32_e32 v76, v76, v60
	v_pk_fma_f32 v[60:61], v[52:53], v[192:193], v[64:65] op_sel_hi:[1,0,1] neg_lo:[1,0,0] neg_hi:[1,0,0]
	s_nop 0
	v_pk_fma_f32 v[60:61], v[60:61], v[194:195], v[56:57] op_sel_hi:[1,0,1]
	s_nop 0
	v_mul_f32_e32 v64, 0xbfb8aa3b, v61
	v_exp_f32_e32 v64, v64
	s_nop 0
	v_add_f32_e32 v64, 1.0, v64
	v_rcp_f32_e32 v64, v64
	s_nop 0
	v_mul_f32_e32 v61, v61, v64
	v_mul_f32_e32 v77, v60, v61
	v_mov_b32_e32 v60, v62
	v_mov_b32_e32 v61, v66
	v_pk_fma_f32 v[60:61], v[132:133], v[192:193], v[60:61] op_sel_hi:[1,0,1] neg_lo:[1,0,0] neg_hi:[1,0,0]
	v_mov_b32_e32 v66, v63
	v_pk_fma_f32 v[60:61], v[60:61], v[194:195], v[136:137] op_sel_hi:[1,0,1]
	v_lshl_add_u64 v[64:65], v[84:85], 0, v[134:135]
	v_mul_f32_e32 v62, 0xbfb8aa3b, v61
	v_exp_f32_e32 v62, v62
	s_nop 0
	v_add_f32_e32 v62, 1.0, v62
	v_rcp_f32_e32 v62, v62
	s_nop 0
	v_mul_f32_e32 v61, v61, v62
	v_mul_f32_e32 v81, v60, v61
	v_pk_fma_f32 v[60:61], v[54:55], v[192:193], v[66:67] op_sel_hi:[1,0,1] neg_lo:[1,0,0] neg_hi:[1,0,0]
	s_nop 0
	v_pk_fma_f32 v[60:61], v[60:61], v[194:195], v[58:59] op_sel_hi:[1,0,1]
	s_nop 0
	v_mul_f32_e32 v62, 0xbfb8aa3b, v61
	v_exp_f32_e32 v62, v62
	s_nop 0
	v_add_f32_e32 v62, 1.0, v62
	v_rcp_f32_e32 v62, v62
	s_nop 0
	v_mul_f32_e32 v61, v61, v62
	v_mul_f32_e32 v63, v60, v61
	v_cvt_pk_bf16_f32 v60, v86, v80
	v_cvt_pk_bf16_f32 v61, v78, v79
	v_cvt_pk_bf16_f32 v62, v76, v77
	v_cvt_pk_bf16_f32 v63, v81, v63
	global_store_dwordx4 v[64:65], v[60:63], off
	s_nop 1
	v_mov_b32_e32 v62, v44
	v_mov_b32_e32 v63, v48
	v_pk_fma_f32 v[62:63], v[188:189], v[182:183], v[62:63] op_sel_hi:[1,0,1] neg_lo:[1,0,0] neg_hi:[1,0,0]
	v_mov_b32_e32 v48, v45
	v_pk_fma_f32 v[62:63], v[62:63], v[184:185], v[190:191] op_sel_hi:[1,0,1]
	v_add_u32_e32 v60, 0x90, v213
	v_mul_f32_e32 v44, 0xbfb8aa3b, v63
	v_exp_f32_e32 v44, v44
	v_mad_i64_i32 v[60:61], s[10:11], v60, s51, v[186:187]
	v_add_f32_e32 v44, 1.0, v44
	v_rcp_f32_e32 v44, v44
	s_nop 0
	v_mul_f32_e32 v44, v63, v44
	v_mul_f32_e32 v62, v62, v44
	v_pk_fma_f32 v[44:45], v[68:69], v[182:183], v[48:49] op_sel_hi:[1,0,1] neg_lo:[1,0,0] neg_hi:[1,0,0]
	s_nop 0
	v_pk_fma_f32 v[44:45], v[44:45], v[184:185], v[72:73] op_sel_hi:[1,0,1]
	s_nop 0
	v_mul_f32_e32 v48, 0xbfb8aa3b, v45
	v_exp_f32_e32 v48, v48
	s_nop 0
	v_add_f32_e32 v48, 1.0, v48
	v_rcp_f32_e32 v48, v48
	s_nop 0
	v_mul_f32_e32 v45, v45, v48
	v_mul_f32_e32 v48, v44, v45
	v_mov_b32_e32 v44, v46
	v_mov_b32_e32 v45, v50
	v_pk_fma_f32 v[44:45], v[140:141], v[182:183], v[44:45] op_sel_hi:[1,0,1] neg_lo:[1,0,0] neg_hi:[1,0,0]
	v_mov_b32_e32 v50, v47
	v_pk_fma_f32 v[44:45], v[44:45], v[184:185], v[144:145] op_sel_hi:[1,0,1]
	s_nop 0
	v_mul_f32_e32 v46, 0xbfb8aa3b, v45
	v_exp_f32_e32 v46, v46
	s_nop 0
	v_add_f32_e32 v46, 1.0, v46
	v_rcp_f32_e32 v46, v46
	s_nop 0
	v_mul_f32_e32 v45, v45, v46
	v_mul_f32_e32 v46, v44, v45
	v_pk_fma_f32 v[44:45], v[70:71], v[182:183], v[50:51] op_sel_hi:[1,0,1] neg_lo:[1,0,0] neg_hi:[1,0,0]
	s_nop 0
	v_pk_fma_f32 v[44:45], v[44:45], v[184:185], v[74:75] op_sel_hi:[1,0,1]
	s_nop 0
	v_mul_f32_e32 v47, 0xbfb8aa3b, v45
	v_exp_f32_e32 v47, v47
	s_nop 0
	v_add_f32_e32 v47, 1.0, v47
	v_rcp_f32_e32 v47, v47
	s_nop 0
	v_mul_f32_e32 v45, v45, v47
	v_mul_f32_e32 v47, v44, v45
	v_mov_b32_e32 v44, v36
	v_mov_b32_e32 v45, v40
	v_pk_fma_f32 v[44:45], v[142:143], v[182:183], v[44:45] op_sel_hi:[1,0,1] neg_lo:[1,0,0] neg_hi:[1,0,0]
	v_mov_b32_e32 v40, v37
	v_pk_fma_f32 v[44:45], v[44:45], v[184:185], v[146:147] op_sel_hi:[1,0,1]
	s_nop 0
	v_mul_f32_e32 v36, 0xbfb8aa3b, v45
	v_exp_f32_e32 v36, v36
	s_nop 0
	v_add_f32_e32 v36, 1.0, v36
	v_rcp_f32_e32 v36, v36
	s_nop 0
	v_mul_f32_e32 v36, v45, v36
	v_mul_f32_e32 v44, v44, v36
	v_pk_fma_f32 v[36:37], v[52:53], v[182:183], v[40:41] op_sel_hi:[1,0,1] neg_lo:[1,0,0] neg_hi:[1,0,0]
	s_nop 0
	v_pk_fma_f32 v[36:37], v[36:37], v[184:185], v[56:57] op_sel_hi:[1,0,1]
	s_nop 0
	v_mul_f32_e32 v40, 0xbfb8aa3b, v37
	v_exp_f32_e32 v40, v40
	s_nop 0
	v_add_f32_e32 v40, 1.0, v40
	v_rcp_f32_e32 v40, v40
	s_nop 0
	v_mul_f32_e32 v37, v37, v40
	v_mul_f32_e32 v45, v36, v37
	v_mov_b32_e32 v36, v38
	v_mov_b32_e32 v37, v42
	v_pk_fma_f32 v[36:37], v[132:133], v[182:183], v[36:37] op_sel_hi:[1,0,1] neg_lo:[1,0,0] neg_hi:[1,0,0]
	v_mov_b32_e32 v42, v39
	v_pk_fma_f32 v[36:37], v[36:37], v[184:185], v[136:137] op_sel_hi:[1,0,1]
	v_lshl_add_u64 v[40:41], v[60:61], 0, v[134:135]
	v_mul_f32_e32 v38, 0xbfb8aa3b, v37
	v_exp_f32_e32 v38, v38
	s_nop 0
	v_add_f32_e32 v38, 1.0, v38
	v_rcp_f32_e32 v38, v38
	s_nop 0
	v_mul_f32_e32 v37, v37, v38
	v_mul_f32_e32 v49, v36, v37
	v_pk_fma_f32 v[36:37], v[54:55], v[182:183], v[42:43] op_sel_hi:[1,0,1] neg_lo:[1,0,0] neg_hi:[1,0,0]
	s_nop 0
	v_pk_fma_f32 v[36:37], v[36:37], v[184:185], v[58:59] op_sel_hi:[1,0,1]
	s_nop 0
	v_mul_f32_e32 v38, 0xbfb8aa3b, v37
	v_exp_f32_e32 v38, v38
	s_nop 0
	v_add_f32_e32 v38, 1.0, v38
	v_rcp_f32_e32 v38, v38
	s_nop 0
	v_mul_f32_e32 v37, v37, v38
	v_mul_f32_e32 v39, v36, v37
	v_cvt_pk_bf16_f32 v36, v62, v48
	v_cvt_pk_bf16_f32 v37, v46, v47
	v_cvt_pk_bf16_f32 v38, v44, v45
	v_cvt_pk_bf16_f32 v39, v49, v39
	global_store_dwordx4 v[40:41], v[36:39], off
	s_nop 1
	v_mov_b32_e32 v38, v28
	v_mov_b32_e32 v39, v32
	v_pk_fma_f32 v[38:39], v[188:189], v[176:177], v[38:39] op_sel_hi:[1,0,1] neg_lo:[1,0,0] neg_hi:[1,0,0]
	v_mov_b32_e32 v32, v29
	v_pk_fma_f32 v[38:39], v[38:39], v[178:179], v[190:191] op_sel_hi:[1,0,1]
	v_add_u32_e32 v36, 0xa0, v213
; __device__ __forceinline__ unsigned cvt_pk_bf16(float lo, float hi) { unsigned r; asm volatile("v_cvt_pk_bf16_f32 %0, %1, %2" : "=v"(r) : "v"(lo), "v"(hi)); return r; }
; #define PG8_BAR __builtin_amdgcn_s_barrier()
;     __device__ __forceinline__ void operator()(const f32x4 (&acc)[2][2][4][2], const Unit& u, int wr, int wc, int fr, int fq) const {
;     ...
;             for (int m = 0; m < 4; ++m) { const int row = row0 + ai * HALF + m * 16; bf16_t* rowp = H + (size_t)row * DFF + col0;
;                 const float mean = mean8[ai][m], rstd = rstd8[ai][m];
;                 float h[8];
; #pragma unroll
;                 for (int n = 0; n < 2; ++n) { const f32x4 gq = (acc[ai][0][m][n] - k1[0][n] * mean) * rstd + k2[0][n], uq = (acc[ai][1][m][n] - k1[1][n] * mean) * rstd + k2[1][n];
; #pragma unroll
;                     for (int j = 0; j < 4; ++j) h[n * 4 + j] = gq[j] * __builtin_amdgcn_rcpf(1.f + __expf(-gq[j])) * uq[j]; }
;                 u32x4 w; w.x = cvt_pk_bf16(h[0], h[1]); w.y = cvt_pk_bf16(h[2], h[3]); w.z = cvt_pk_bf16(h[4], h[5]); w.w = cvt_pk_bf16(h[6], h[7]);
;                 *(u32x4*)rowp = w; }
; template <class Epi, bool ALIGN_EPI>
; __device__ __forceinline__ void gemm_phase(LAS unsigned char* lds, const Gemm g, const Order& S, const Epi& E) {
;     ...
;         if constexpr (ALIGN_EPI) { if (wr == 0) PG8_BAR; }
;         if constexpr (!Epi::AFTER_DRAIN) E(acc, cur, wr, wc, fr, fq);
;         if (!has_next) break;
; #pragma unroll
;         for (int a = 0; a < 2; ++a)
; #pragma unroll
;             for (int b = 0; b < 2; ++b)
; #pragma unroll
;                 for (int m = 0; m < 4; ++m)
; #pragma unroll
;                     for (int n = 0; n < 2; ++n) acc[a][b][m][n] = (f32x4){0.f, 0.f, 0.f, 0.f};
;         cur = nxt; cA = nA; cB = nB; ++ui;
;         if constexpr (ALIGN_EPI) { if (wr == 1) PG8_BAR; }
	v_mul_f32_e32 v28, 0xbfb8aa3b, v39
	v_exp_f32_e32 v28, v28
	v_mad_i64_i32 v[36:37], s[10:11], v36, s51, v[186:187]
	v_add_f32_e32 v28, 1.0, v28
	v_rcp_f32_e32 v28, v28
	s_nop 0
	v_mul_f32_e32 v28, v39, v28
	v_mul_f32_e32 v38, v38, v28
	v_pk_fma_f32 v[28:29], v[68:69], v[176:177], v[32:33] op_sel_hi:[1,0,1] neg_lo:[1,0,0] neg_hi:[1,0,0]
	s_nop 0
	v_pk_fma_f32 v[28:29], v[28:29], v[178:179], v[72:73] op_sel_hi:[1,0,1]
	s_nop 0
	v_mul_f32_e32 v32, 0xbfb8aa3b, v29
	v_exp_f32_e32 v32, v32
	s_nop 0
	v_add_f32_e32 v32, 1.0, v32
	v_rcp_f32_e32 v32, v32
	s_nop 0
	v_mul_f32_e32 v29, v29, v32
	v_mul_f32_e32 v32, v28, v29
	v_mov_b32_e32 v28, v30
	v_mov_b32_e32 v29, v34
	v_pk_fma_f32 v[28:29], v[140:141], v[176:177], v[28:29] op_sel_hi:[1,0,1] neg_lo:[1,0,0] neg_hi:[1,0,0]
	v_mov_b32_e32 v34, v31
	v_pk_fma_f32 v[28:29], v[28:29], v[178:179], v[144:145] op_sel_hi:[1,0,1]
	s_nop 0
	v_mul_f32_e32 v30, 0xbfb8aa3b, v29
	v_exp_f32_e32 v30, v30
	s_nop 0
	v_add_f32_e32 v30, 1.0, v30
	v_rcp_f32_e32 v30, v30
	s_nop 0
	v_mul_f32_e32 v29, v29, v30
	v_mul_f32_e32 v30, v28, v29
	v_pk_fma_f32 v[28:29], v[70:71], v[176:177], v[34:35] op_sel_hi:[1,0,1] neg_lo:[1,0,0] neg_hi:[1,0,0]
	s_nop 0
	v_pk_fma_f32 v[28:29], v[28:29], v[178:179], v[74:75] op_sel_hi:[1,0,1]
	s_nop 0
	v_mul_f32_e32 v31, 0xbfb8aa3b, v29
	v_exp_f32_e32 v31, v31
	s_nop 0
	v_add_f32_e32 v31, 1.0, v31
	v_rcp_f32_e32 v31, v31
	s_nop 0
	v_mul_f32_e32 v29, v29, v31
	v_mul_f32_e32 v31, v28, v29
	v_mov_b32_e32 v28, v20
	v_mov_b32_e32 v29, v24
	v_pk_fma_f32 v[28:29], v[142:143], v[176:177], v[28:29] op_sel_hi:[1,0,1] neg_lo:[1,0,0] neg_hi:[1,0,0]
	v_mov_b32_e32 v24, v21
	v_pk_fma_f32 v[28:29], v[28:29], v[178:179], v[146:147] op_sel_hi:[1,0,1]
	s_nop 0
	v_mul_f32_e32 v20, 0xbfb8aa3b, v29
	v_exp_f32_e32 v20, v20
	s_nop 0
	v_add_f32_e32 v20, 1.0, v20
	v_rcp_f32_e32 v20, v20
	s_nop 0
	v_mul_f32_e32 v20, v29, v20
	v_mul_f32_e32 v28, v28, v20
	v_pk_fma_f32 v[20:21], v[52:53], v[176:177], v[24:25] op_sel_hi:[1,0,1] neg_lo:[1,0,0] neg_hi:[1,0,0]
	s_nop 0
	v_pk_fma_f32 v[20:21], v[20:21], v[178:179], v[56:57] op_sel_hi:[1,0,1]
	s_nop 0
	v_mul_f32_e32 v24, 0xbfb8aa3b, v21
	v_exp_f32_e32 v24, v24
	s_nop 0
	v_add_f32_e32 v24, 1.0, v24
	v_rcp_f32_e32 v24, v24
	s_nop 0
	v_mul_f32_e32 v21, v21, v24
	v_mul_f32_e32 v29, v20, v21
	v_mov_b32_e32 v20, v22
	v_mov_b32_e32 v21, v26
	v_pk_fma_f32 v[20:21], v[132:133], v[176:177], v[20:21] op_sel_hi:[1,0,1] neg_lo:[1,0,0] neg_hi:[1,0,0]
	v_mov_b32_e32 v26, v23
	v_pk_fma_f32 v[20:21], v[20:21], v[178:179], v[136:137] op_sel_hi:[1,0,1]
	v_lshl_add_u64 v[24:25], v[36:37], 0, v[134:135]
	v_mul_f32_e32 v22, 0xbfb8aa3b, v21
	v_exp_f32_e32 v22, v22
	s_nop 0
	v_add_f32_e32 v22, 1.0, v22
	v_rcp_f32_e32 v22, v22
	s_nop 0
	v_mul_f32_e32 v21, v21, v22
	v_mul_f32_e32 v33, v20, v21
	v_pk_fma_f32 v[20:21], v[54:55], v[176:177], v[26:27] op_sel_hi:[1,0,1] neg_lo:[1,0,0] neg_hi:[1,0,0]
	s_nop 0
	v_pk_fma_f32 v[20:21], v[20:21], v[178:179], v[58:59] op_sel_hi:[1,0,1]
	s_nop 0
	v_mul_f32_e32 v22, 0xbfb8aa3b, v21
	v_exp_f32_e32 v22, v22
	s_nop 0
	v_add_f32_e32 v22, 1.0, v22
	v_rcp_f32_e32 v22, v22
	s_nop 0
	v_mul_f32_e32 v21, v21, v22
	v_mul_f32_e32 v23, v20, v21
	v_cvt_pk_bf16_f32 v20, v38, v32
	v_cvt_pk_bf16_f32 v21, v30, v31
	v_cvt_pk_bf16_f32 v22, v28, v29
	v_cvt_pk_bf16_f32 v23, v33, v23
	global_store_dwordx4 v[24:25], v[20:23], off
	s_nop 1
	v_mov_b32_e32 v22, v12
	v_mov_b32_e32 v23, v16
	v_pk_fma_f32 v[22:23], v[188:189], v[174:175], v[22:23] op_sel_hi:[1,0,1] neg_lo:[1,0,0] neg_hi:[1,0,0]
	v_mov_b32_e32 v16, v13
	v_pk_fma_f32 v[22:23], v[22:23], v[180:181], v[190:191] op_sel_hi:[1,0,1]
	v_add_u32_e32 v20, 0xb0, v213
	v_mul_f32_e32 v12, 0xbfb8aa3b, v23
	v_exp_f32_e32 v12, v12
	v_mad_i64_i32 v[20:21], s[10:11], v20, s51, v[186:187]
	v_add_f32_e32 v12, 1.0, v12
	v_rcp_f32_e32 v12, v12
	s_nop 0
	v_mul_f32_e32 v12, v23, v12
	v_mul_f32_e32 v22, v22, v12
	v_pk_fma_f32 v[12:13], v[68:69], v[174:175], v[16:17] op_sel_hi:[1,0,1] neg_lo:[1,0,0] neg_hi:[1,0,0]
	s_nop 0
	v_pk_fma_f32 v[12:13], v[12:13], v[180:181], v[72:73] op_sel_hi:[1,0,1]
	s_nop 0
	v_mul_f32_e32 v16, 0xbfb8aa3b, v13
	v_exp_f32_e32 v16, v16
	s_nop 0
	v_add_f32_e32 v16, 1.0, v16
	v_rcp_f32_e32 v16, v16
	s_nop 0
	v_mul_f32_e32 v13, v13, v16
	v_mul_f32_e32 v16, v12, v13
	v_mov_b32_e32 v12, v14
	v_mov_b32_e32 v13, v18
	v_pk_fma_f32 v[12:13], v[140:141], v[174:175], v[12:13] op_sel_hi:[1,0,1] neg_lo:[1,0,0] neg_hi:[1,0,0]
	v_mov_b32_e32 v18, v15
	v_pk_fma_f32 v[12:13], v[12:13], v[180:181], v[144:145] op_sel_hi:[1,0,1]
	s_nop 0
	v_mul_f32_e32 v14, 0xbfb8aa3b, v13
	v_exp_f32_e32 v14, v14
	s_nop 0
	v_add_f32_e32 v14, 1.0, v14
	v_rcp_f32_e32 v14, v14
	s_nop 0
	v_mul_f32_e32 v13, v13, v14
	v_mul_f32_e32 v14, v12, v13
	v_pk_fma_f32 v[12:13], v[70:71], v[174:175], v[18:19] op_sel_hi:[1,0,1] neg_lo:[1,0,0] neg_hi:[1,0,0]
	s_nop 0
	v_pk_fma_f32 v[12:13], v[12:13], v[180:181], v[74:75] op_sel_hi:[1,0,1]
	s_nop 0
	v_mul_f32_e32 v15, 0xbfb8aa3b, v13
	v_exp_f32_e32 v15, v15
	s_nop 0
	v_add_f32_e32 v15, 1.0, v15
	v_rcp_f32_e32 v15, v15
	s_nop 0
	v_mul_f32_e32 v13, v13, v15
	v_mul_f32_e32 v15, v12, v13
	v_mov_b32_e32 v12, v4
	v_mov_b32_e32 v13, v8
	v_pk_fma_f32 v[12:13], v[142:143], v[174:175], v[12:13] op_sel_hi:[1,0,1] neg_lo:[1,0,0] neg_hi:[1,0,0]
	v_mov_b32_e32 v8, v5
	v_pk_fma_f32 v[12:13], v[12:13], v[180:181], v[146:147] op_sel_hi:[1,0,1]
	s_nop 0
	v_mul_f32_e32 v4, 0xbfb8aa3b, v13
	v_exp_f32_e32 v4, v4
	s_nop 0
	v_add_f32_e32 v4, 1.0, v4
	v_rcp_f32_e32 v4, v4
	s_nop 0
	v_mul_f32_e32 v4, v13, v4
	v_mul_f32_e32 v12, v12, v4
	v_pk_fma_f32 v[4:5], v[52:53], v[174:175], v[8:9] op_sel_hi:[1,0,1] neg_lo:[1,0,0] neg_hi:[1,0,0]
	s_nop 0
	v_pk_fma_f32 v[4:5], v[4:5], v[180:181], v[56:57] op_sel_hi:[1,0,1]
	s_nop 0
	v_mul_f32_e32 v8, 0xbfb8aa3b, v5
	v_exp_f32_e32 v8, v8
	s_nop 0
	v_add_f32_e32 v8, 1.0, v8
	v_rcp_f32_e32 v8, v8
	s_nop 0
	v_mul_f32_e32 v5, v5, v8
	v_mul_f32_e32 v13, v4, v5
	v_mov_b32_e32 v4, v6
	v_mov_b32_e32 v5, v10
	v_pk_fma_f32 v[4:5], v[132:133], v[174:175], v[4:5] op_sel_hi:[1,0,1] neg_lo:[1,0,0] neg_hi:[1,0,0]
	v_mov_b32_e32 v10, v7
	v_pk_fma_f32 v[4:5], v[4:5], v[180:181], v[136:137] op_sel_hi:[1,0,1]
	v_lshl_add_u64 v[8:9], v[20:21], 0, v[134:135]
	v_mul_f32_e32 v6, 0xbfb8aa3b, v5
	v_exp_f32_e32 v6, v6
	s_nop 0
	v_add_f32_e32 v6, 1.0, v6
	v_rcp_f32_e32 v6, v6
	s_nop 0
	v_mul_f32_e32 v5, v5, v6
	v_mul_f32_e32 v17, v4, v5
	v_pk_fma_f32 v[4:5], v[54:55], v[174:175], v[10:11] op_sel_hi:[1,0,1] neg_lo:[1,0,0] neg_hi:[1,0,0]
	s_nop 0
	v_pk_fma_f32 v[4:5], v[4:5], v[180:181], v[58:59] op_sel_hi:[1,0,1]
	s_nop 0
	v_mul_f32_e32 v6, 0xbfb8aa3b, v5
	v_exp_f32_e32 v6, v6
	s_nop 0
	v_add_f32_e32 v6, 1.0, v6
	v_rcp_f32_e32 v6, v6
	s_nop 0
	v_mul_f32_e32 v5, v5, v6
	v_mul_f32_e32 v7, v4, v5
	v_cvt_pk_bf16_f32 v4, v22, v16
	v_cvt_pk_bf16_f32 v5, v14, v15
	v_cvt_pk_bf16_f32 v6, v12, v13
	v_cvt_pk_bf16_f32 v7, v17, v7
	global_store_dwordx4 v[8:9], v[4:7], off
	s_cbranch_vccnz .LBB0_1138
	s_andn2_b64 vcc, exec, s[4:5]
	s_cbranch_vccnz .LBB0_1137
	s_barrier
	s_branch .LBB0_1137
